# static s_setprio 1 for waves 0-3 (other half) in every GEMM tile loop, flips removed (A/B against v31)
# baseline (speedup 1.0000x reference)
.LBB0_34:
	s_lshl_b32 s6, s6, 5
	s_and_b32 s13, s6, 0x60
	s_mov_b64 s[6:7], 0x80
	s_add_i32 m0, s9, 0x18000
	v_lshl_add_u64 v[6:7], v[6:7], 0, s[6:7]
	s_lshl_b32 s12, s5, 13
	s_lshl_b32 s14, s13, 7
	s_waitcnt vmcnt(4)
	s_barrier
	global_load_lds_dwordx4 v[6:7], off
	v_lshl_add_u64 v[4:5], v[4:5], 0, s[6:7]
	s_add_i32 m0, s9, 0x1a000
	s_add_i32 s71, s9, 0x8000
	s_add_i32 s72, s9, 0xa000
	global_load_lds_dwordx4 v[4:5], off
	v_lshl_add_u64 v[2:3], v[2:3], 0, s[6:7]
	s_mov_b32 m0, s71
	s_add_u32 s10, s90, 0x40080
	global_load_lds_dwordx4 v[2:3], off
	v_lshl_add_u64 v[0:1], v[0:1], 0, s[6:7]
	s_mov_b32 m0, s72
	s_addc_u32 s11, s91, 0
	global_load_lds_dwordx4 v[0:1], off
	s_add_i32 m0, s9, 0x1c000
	v_lshl_add_u64 v[0:1], s[10:11], 0, v[132:133]
	global_load_lds_dwordx4 v[0:1], off
	v_lshl_add_u64 v[0:1], s[10:11], 0, v[128:129]
	s_add_i32 m0, s9, 0x1e000
	s_add_i32 s74, 0, 0x10000
	global_load_lds_dwordx4 v[0:1], off
	v_lshrrev_b32_e32 v1, 1, v8
	v_and_b32_e32 v1, 24, v1
	v_and_b32_e32 v0, 15, v8
	v_lshlrev_b32_e32 v2, 1, v1
	v_lshl_or_b32 v144, s5, 6, v0
	v_lshl_or_b32 v0, v0, 6, v2
	v_lshlrev_b32_e32 v2, 2, v8
	v_and_b32_e32 v2, 32, v2
	v_bitop3_b32 v3, v0, s12, v2 bitop3:0xde
	v_bitop3_b32 v145, v0, s14, v2 bitop3:0xde
	v_lshlrev_b32_e32 v0, 14, v13
	v_and_b32_e32 v0, 0xffff8000, v0
	v_or_b32_e32 v146, s13, v1
	v_lshl_add_u32 v0, v12, 11, v0
	v_and_b32_e32 v1, 1, v13
	v_lshl_or_b32 v0, v1, 6, v0
	v_lshl_add_u32 v136, v14, 1, v0
	v_lshlrev_b32_e32 v0, 14, v9
	v_and_b32_e32 v0, 0xffff8000, v0
	s_waitcnt vmcnt(6)
	v_lshl_add_u32 v0, v10, 11, v0
	v_and_b32_e32 v1, 1, v9
	v_lshl_or_b32 v0, v1, 6, v0
	s_add_i32 s75, 0, 0x14000
	s_sext_i32_i8 s77, s4
	s_ashr_i32 s73, s3, 31
	v_mov_b32_e32 v137, v133
	v_lshl_add_u32 v138, v11, 1, v0
	v_mov_b32_e32 v139, v133
	v_mov_b64_e32 v[140:141], 0x1680
	v_mov_b64_e32 v[142:143], 0x167f
	v_add_u32_e32 v147, s74, v145
	v_add_u32_e32 v148, 0, v3
	v_add_u32_e32 v149, s75, v145
	s_movk_i32 s76, 0x1e00
	s_barrier
	v_readfirstlane_b32 s4, v154
	s_bitcmp1_b32 s4, 8
	s_cbranch_scc1 .Lprio_35
	s_setprio 1

.LBB0_543:
	s_lshl_b32 s6, s6, 5
	s_and_b32 s25, s6, 0x60
	s_mov_b64 s[6:7], 0x80
	s_add_i32 m0, s51, 0x18000
	v_lshl_add_u64 v[6:7], v[6:7], 0, s[6:7]
	s_lshl_b32 s24, s5, 13
	s_lshl_b32 s40, s25, 7
	s_waitcnt vmcnt(4)
	s_barrier
	global_load_lds_dwordx4 v[6:7], off
	v_lshl_add_u64 v[4:5], v[4:5], 0, s[6:7]
	s_add_i32 m0, s51, 0x1a000
	s_add_i32 s76, s51, 0x8000
	s_add_i32 s77, s51, 0xa000
	global_load_lds_dwordx4 v[4:5], off
	v_lshl_add_u64 v[2:3], v[2:3], 0, s[6:7]
	s_mov_b32 m0, s76
	s_add_u32 s14, s52, 0x10080
	global_load_lds_dwordx4 v[2:3], off
	v_lshl_add_u64 v[0:1], v[0:1], 0, s[6:7]
	s_mov_b32 m0, s77
	s_addc_u32 s15, s53, 0
	global_load_lds_dwordx4 v[0:1], off
	s_add_i32 m0, s51, 0x1c000
	v_lshl_add_u64 v[0:1], s[14:15], 0, v[132:133]
	global_load_lds_dwordx4 v[0:1], off
	v_lshl_add_u64 v[0:1], s[14:15], 0, v[128:129]
	s_add_i32 m0, s51, 0x1e000
	s_add_i32 s79, 0, 0x10000
	global_load_lds_dwordx4 v[0:1], off
	v_lshrrev_b32_e32 v1, 1, v8
	v_and_b32_e32 v1, 24, v1
	v_and_b32_e32 v0, 15, v8
	v_lshlrev_b32_e32 v2, 1, v1
	v_lshl_or_b32 v146, s5, 6, v0
	v_lshl_or_b32 v0, v0, 6, v2
	v_lshlrev_b32_e32 v2, 2, v8
	v_and_b32_e32 v2, 32, v2
	s_waitcnt vmcnt(6)
	v_bitop3_b32 v3, v0, s24, v2 bitop3:0xde
	v_bitop3_b32 v147, v0, s40, v2 bitop3:0xde
	s_sext_i32_i8 s81, s4
	s_ashr_i32 s78, s3, 31
	v_or_b32_e32 v148, s25, v1
	v_mov_b64_e32 v[136:137], 0x600
	v_mov_b64_e32 v[138:139], 0x5ff
	v_add_u32_e32 v149, s79, v147
	v_add_u32_e32 v150, 0, v3
	v_add_u32_e32 v151, s72, v147
	s_mov_b64 s[14:15], 0x58000
	s_mov_b32 s80, 0x58000
	s_barrier
	v_readfirstlane_b32 s4, v154
	s_bitcmp1_b32 s4, 8
	s_cbranch_scc1 .Lprio_544
	s_setprio 1

.LBB0_565:
	s_lshl_b32 s8, s8, 5
	s_and_b32 s25, s8, 0x60
	s_mov_b64 s[8:9], 0x80
	s_add_i32 m0, s57, 0x18000
	v_lshl_add_u64 v[6:7], v[6:7], 0, s[8:9]
	s_lshl_b32 s24, s5, 13
	s_lshl_b32 s40, s25, 7
	s_waitcnt vmcnt(4)
	s_barrier
	global_load_lds_dwordx4 v[6:7], off
	v_lshl_add_u64 v[4:5], v[4:5], 0, s[8:9]
	s_add_i32 m0, s57, 0x1a000
	s_add_i32 s69, s57, 0x8000
	s_add_i32 s70, s57, 0xa000
	global_load_lds_dwordx4 v[4:5], off
	v_lshl_add_u64 v[2:3], v[2:3], 0, s[8:9]
	s_mov_b32 m0, s69
	s_add_u32 s14, s60, 0x40080
	global_load_lds_dwordx4 v[2:3], off
	v_lshl_add_u64 v[0:1], v[0:1], 0, s[8:9]
	s_mov_b32 m0, s70
	s_addc_u32 s15, s61, 0
	global_load_lds_dwordx4 v[0:1], off
	s_add_i32 m0, s57, 0x1c000
	v_lshl_add_u64 v[0:1], s[14:15], 0, v[132:133]
	global_load_lds_dwordx4 v[0:1], off
	v_lshl_add_u64 v[0:1], s[14:15], 0, v[128:129]
	s_add_i32 m0, s57, 0x1e000
	s_add_i32 s73, 0, 0x10000
	global_load_lds_dwordx4 v[0:1], off
	v_lshrrev_b32_e32 v1, 1, v9
	v_and_b32_e32 v1, 24, v1
	v_and_b32_e32 v0, 15, v9
	v_lshlrev_b32_e32 v2, 1, v1
	v_lshl_or_b32 v152, s5, 6, v0
	v_lshl_or_b32 v0, v0, 6, v2
	v_lshlrev_b32_e32 v2, 2, v9
	v_and_b32_e32 v2, 32, v2
	v_bitop3_b32 v3, v0, s24, v2 bitop3:0xde
	v_bitop3_b32 v153, v0, s40, v2 bitop3:0xde
	v_lshlrev_b32_e32 v0, 14, v13
	v_and_b32_e32 v0, 0xffff8000, v0
	v_or_b32_e32 v156, s25, v1
	v_lshl_add_u32 v0, v12, 11, v0
	v_and_b32_e32 v1, 1, v13
	v_lshl_or_b32 v0, v1, 6, v0
	v_lshl_add_u32 v136, v14, 1, v0
	v_lshlrev_b32_e32 v0, 14, v8
	v_and_b32_e32 v0, 0xffff8000, v0
	s_waitcnt vmcnt(6)
	v_lshl_add_u32 v0, v10, 11, v0
	v_and_b32_e32 v1, 1, v8
	v_lshl_or_b32 v0, v1, 6, v0
	s_sext_i32_i8 s78, s4
	s_ashr_i32 s71, s3, 31
	v_mov_b32_e32 v137, v133
	v_lshl_add_u32 v138, v11, 1, v0
	v_mov_b32_e32 v139, v133
	v_mov_b64_e32 v[140:141], 0xc00
	v_mov_b64_e32 v[142:143], 0xbff
	v_add_u32_e32 v157, s73, v153
	v_add_u32_e32 v158, 0, v3
	v_add_u32_e32 v159, s72, v153
	s_mov_b64 s[14:15], 0x80000
	s_mov_b32 s74, 0x80000
	s_mov_b64 s[24:25], 0x90000
	s_mov_b32 s75, 0x90000
	s_mov_b64 s[40:41], 0xa0000
	s_mov_b32 s76, 0xa0000
	s_mov_b64 s[46:47], 0xb0000
	s_mov_b32 s77, 0xb0000
	s_barrier
	v_readfirstlane_b32 s4, v154
	s_bitcmp1_b32 s4, 8
	s_cbranch_scc1 .Lprio_566
	s_setprio 1

.LBB0_587:
	s_lshl_b32 s20, s20, 5
	s_and_b32 s41, s20, 0x60
	s_mov_b64 s[20:21], 0x80
	s_add_i32 m0, s35, 0x18000
	v_lshl_add_u64 v[6:7], v[6:7], 0, s[20:21]
	s_lshl_b32 s40, s5, 13
	s_lshl_b32 s44, s41, 7
	s_waitcnt vmcnt(4)
	s_barrier
	global_load_lds_dwordx4 v[6:7], off
	v_lshl_add_u64 v[4:5], v[4:5], 0, s[20:21]
	s_add_i32 m0, s35, 0x1a000
	s_add_i32 s59, s35, 0x8000
	s_add_i32 s60, s35, 0xa000
	global_load_lds_dwordx4 v[4:5], off
	v_lshl_add_u64 v[2:3], v[2:3], 0, s[20:21]
	s_mov_b32 m0, s59
	s_add_u32 s24, s52, 0x20080
	global_load_lds_dwordx4 v[2:3], off
	v_lshl_add_u64 v[0:1], v[0:1], 0, s[20:21]
	s_mov_b32 m0, s60
	s_addc_u32 s25, s53, 0
	global_load_lds_dwordx4 v[0:1], off
	s_add_i32 m0, s35, 0x1c000
	v_lshl_add_u64 v[0:1], s[24:25], 0, v[132:133]
	global_load_lds_dwordx4 v[0:1], off
	v_lshl_add_u64 v[0:1], s[24:25], 0, v[128:129]
	s_add_i32 m0, s35, 0x1e000
	s_add_i32 s62, 0, 0x10000
	global_load_lds_dwordx4 v[0:1], off
	v_lshrrev_b32_e32 v1, 1, v9
	v_and_b32_e32 v1, 24, v1
	v_and_b32_e32 v0, 15, v9
	v_lshlrev_b32_e32 v2, 1, v1
	v_lshl_or_b32 v148, s5, 6, v0
	v_lshl_or_b32 v0, v0, 6, v2
	v_lshlrev_b32_e32 v2, 2, v9
	v_and_b32_e32 v2, 32, v2
	v_bitop3_b32 v3, v0, s40, v2 bitop3:0xde
	v_bitop3_b32 v149, v0, s44, v2 bitop3:0xde
	v_lshlrev_b32_e32 v0, 13, v13
	v_and_b32_e32 v0, 0xffffc000, v0
	v_or_b32_e32 v150, s41, v1
	v_lshl_add_u32 v0, v12, 10, v0
	v_and_b32_e32 v1, 1, v13
	v_lshl_or_b32 v0, v1, 6, v0
	v_lshl_add_u32 v136, v14, 1, v0
	v_lshlrev_b32_e32 v0, 13, v8
	v_and_b32_e32 v0, 0xffffc000, v0
	s_waitcnt vmcnt(6)
	v_lshl_add_u32 v0, v10, 10, v0
	v_and_b32_e32 v1, 1, v8
	v_lshl_or_b32 v0, v1, 6, v0
	s_sext_i32_i8 s63, s4
	s_ashr_i32 s61, s3, 31
	v_mov_b32_e32 v137, v133
	v_lshl_add_u32 v138, v11, 1, v0
	v_mov_b32_e32 v139, v133
	v_mov_b64_e32 v[140:141], 0x600
	v_mov_b64_e32 v[142:143], 0x5ff
	v_add_u32_e32 v151, s62, v149
	v_add_u32_e32 v152, 0, v3
	v_add_u32_e32 v153, s72, v149
	s_barrier
	v_readfirstlane_b32 s4, v154
	s_bitcmp1_b32 s4, 8
	s_cbranch_scc1 .Lprio_588
	s_setprio 1

.LBB0_599:
	s_lshl_b32 s20, s20, 5
	s_and_b32 s25, s20, 0x60
	s_mov_b64 s[20:21], 0x80
	s_add_i32 m0, s35, 0x18000
	v_lshl_add_u64 v[6:7], v[6:7], 0, s[20:21]
	s_lshl_b32 s24, s5, 13
	s_lshl_b32 s40, s25, 7
	s_waitcnt vmcnt(4)
	s_barrier
	global_load_lds_dwordx4 v[6:7], off
	v_lshl_add_u64 v[4:5], v[4:5], 0, s[20:21]
	s_add_i32 m0, s35, 0x1a000
	s_add_i32 s57, s35, 0x8000
	s_add_i32 s58, s35, 0xa000
	global_load_lds_dwordx4 v[4:5], off
	v_lshl_add_u64 v[2:3], v[2:3], 0, s[20:21]
	s_mov_b32 m0, s57
	s_add_u32 s22, s50, 0x40080
	global_load_lds_dwordx4 v[2:3], off
	v_lshl_add_u64 v[0:1], v[0:1], 0, s[20:21]
	s_mov_b32 m0, s58
	s_addc_u32 s23, s51, 0
	global_load_lds_dwordx4 v[0:1], off
	s_add_i32 m0, s35, 0x1c000
	v_lshl_add_u64 v[0:1], s[22:23], 0, v[132:133]
	global_load_lds_dwordx4 v[0:1], off
	v_lshl_add_u64 v[0:1], s[22:23], 0, v[128:129]
	s_add_i32 m0, s35, 0x1e000
	s_add_i32 s60, 0, 0x10000
	global_load_lds_dwordx4 v[0:1], off
	v_lshrrev_b32_e32 v1, 1, v9
	v_and_b32_e32 v1, 24, v1
	v_and_b32_e32 v0, 15, v9
	v_lshlrev_b32_e32 v2, 1, v1
	v_lshl_or_b32 v150, s5, 6, v0
	v_lshl_or_b32 v0, v0, 6, v2
	v_lshlrev_b32_e32 v2, 2, v9
	v_and_b32_e32 v2, 32, v2
	v_bitop3_b32 v3, v0, s24, v2 bitop3:0xde
	v_bitop3_b32 v151, v0, s40, v2 bitop3:0xde
	v_lshlrev_b32_e32 v0, 14, v13
	v_and_b32_e32 v0, 0xffff8000, v0
	v_or_b32_e32 v152, s25, v1
	v_lshl_add_u32 v0, v12, 11, v0
	v_and_b32_e32 v1, 1, v13
	v_lshl_or_b32 v0, v1, 6, v0
	v_lshl_add_u32 v136, v14, 1, v0
	v_lshlrev_b32_e32 v0, 14, v8
	v_and_b32_e32 v0, 0xffff8000, v0
	s_waitcnt vmcnt(6)
	v_lshl_add_u32 v0, v10, 11, v0
	v_and_b32_e32 v1, 1, v8
	v_lshl_or_b32 v0, v1, 6, v0
	s_sext_i32_i8 s61, s4
	s_ashr_i32 s59, s3, 31
	v_mov_b32_e32 v137, v133
	v_lshl_add_u32 v138, v11, 1, v0
	v_mov_b32_e32 v139, v133
	v_mov_b64_e32 v[140:141], 0x600
	v_mov_b64_e32 v[142:143], 0x5ff
	v_add_u32_e32 v153, s60, v151
	v_add_u32_e32 v156, 0, v3
	v_add_u32_e32 v157, s72, v151
	s_barrier
	v_readfirstlane_b32 s4, v154
	s_bitcmp1_b32 s4, 8
	s_cbranch_scc1 .Lprio_600
	s_setprio 1

.LBB0_624:
	s_or_b64 exec, exec, s[46:47]
	s_and_b64 vcc, exec, s[6:7]
	s_mov_b32 s46, s22
	s_mov_b32 s48, s24
	s_mov_b64 s[52:53], s[44:45]
	s_mov_b64 s[50:51], s[40:41]
	s_cbranch_vccnz .LBB0_677
	v_readfirstlane_b32 s6, v154
	s_bitcmp1_b32 s6, 8
	s_cbranch_scc1 .Lprio_625
	s_setprio 1

.LBB0_693:
	s_lshl_b32 s6, s6, 5
	s_mov_b64 s[14:15], 0x80
	s_and_b32 s17, s6, 0x60
	s_add_i32 m0, s47, 0x18000
	v_lshl_add_u64 v[6:7], v[6:7], 0, s[14:15]
	s_lshl_b32 s16, s5, 13
	s_lshl_b32 s20, s17, 7
	s_waitcnt vmcnt(4)
	s_barrier
	global_load_lds_dwordx4 v[6:7], off
	v_lshl_add_u64 v[4:5], v[4:5], 0, s[14:15]
	s_add_i32 m0, s47, 0x1a000
	s_add_i32 s57, s47, 0x8000
	s_add_i32 s58, s47, 0xa000
	global_load_lds_dwordx4 v[4:5], off
	v_lshl_add_u64 v[2:3], v[2:3], 0, s[14:15]
	s_mov_b32 m0, s57
	s_add_u32 s6, s48, 0x40080
	global_load_lds_dwordx4 v[2:3], off
	v_lshl_add_u64 v[0:1], v[0:1], 0, s[14:15]
	s_mov_b32 m0, s58
	s_addc_u32 s7, s49, 0
	global_load_lds_dwordx4 v[0:1], off
	s_add_i32 m0, s47, 0x1c000
	v_lshl_add_u64 v[0:1], s[6:7], 0, v[132:133]
	global_load_lds_dwordx4 v[0:1], off
	v_lshl_add_u64 v[0:1], s[6:7], 0, v[128:129]
	s_add_i32 m0, s47, 0x1e000
	s_add_i32 s60, 0, 0x10000
	global_load_lds_dwordx4 v[0:1], off
	v_lshrrev_b32_e32 v1, 1, v9
	v_and_b32_e32 v1, 24, v1
	v_and_b32_e32 v0, 15, v9
	v_lshlrev_b32_e32 v2, 1, v1
	v_lshl_or_b32 v152, s5, 6, v0
	v_lshl_or_b32 v0, v0, 6, v2
	v_lshlrev_b32_e32 v2, 2, v9
	v_and_b32_e32 v2, 32, v2
	v_bitop3_b32 v3, v0, s16, v2 bitop3:0xde
	v_bitop3_b32 v153, v0, s20, v2 bitop3:0xde
	v_lshlrev_b32_e32 v0, 14, v13
	v_and_b32_e32 v0, 0xffff8000, v0
	v_or_b32_e32 v156, s17, v1
	v_lshl_add_u32 v0, v12, 11, v0
	v_and_b32_e32 v1, 1, v13
	v_lshl_or_b32 v0, v1, 6, v0
	v_lshl_add_u32 v136, v14, 1, v0
	v_lshlrev_b32_e32 v0, 14, v8
	v_and_b32_e32 v0, 0xffff8000, v0
	s_waitcnt vmcnt(6)
	v_lshl_add_u32 v0, v10, 11, v0
	v_and_b32_e32 v1, 1, v8
	v_lshl_or_b32 v0, v1, 6, v0
	s_sext_i32_i8 s66, s4
	s_ashr_i32 s59, s3, 31
	v_mov_b32_e32 v137, v133
	v_lshl_add_u32 v138, v11, 1, v0
	v_mov_b32_e32 v139, v133
	v_mov_b64_e32 v[140:141], 0x1800
	v_mov_b64_e32 v[142:143], 0x17ff
	v_add_u32_e32 v157, s60, v153
	v_add_u32_e32 v158, 0, v3
	v_add_u32_e32 v159, s72, v153
	v_mov_b32_e32 v160, 0x358637bd
	s_mov_b32 s61, 0x800000
	s_mov_b64 s[16:17], 0x80000
	s_mov_b32 s62, 0x80000
	s_mov_b64 s[20:21], 0x90000
	s_mov_b32 s63, 0x90000
	s_mov_b64 s[22:23], 0xa0000
	s_mov_b32 s64, 0xa0000
	s_mov_b64 s[24:25], 0xb0000
	s_mov_b32 s65, 0xb0000
	s_barrier
	v_readfirstlane_b32 s4, v154
	s_bitcmp1_b32 s4, 8
	s_cbranch_scc1 .Lprio_694
	s_setprio 1

.LBB0_718:
	s_or_b64 exec, exec, s[36:37]
	s_add_u32 s19, s28, s24
	s_addc_u32 s21, s29, s25
	s_and_b64 s[6:7], s[14:15], s[6:7]
	s_and_b64 s[6:7], s[6:7], exec
	s_cselect_b32 s58, s21, s58
	s_cselect_b32 s59, s19, s59
	s_and_b64 vcc, exec, s[4:5]
	s_mov_b32 s36, s18
	s_mov_b32 s38, s20
	s_mov_b64 s[40:41], s[30:31]
	s_mov_b64 s[44:45], s[22:23]
	s_cbranch_vccnz .LBB0_744
	v_readfirstlane_b32 s4, v154
	s_bitcmp1_b32 s4, 8
	s_cbranch_scc1 .Lprio_719
	s_setprio 1
